# v39 + first grid-barrier visit reads the 16 arrival counters with 16 loads in flight
# baseline (speedup 1.0000x reference)
.LBB0_636:
	s_mov_b64 s[4:5], 0
	v_mov_b32_e32 v3, 0
	v_mov_b32_e32 v1, 0
	s_mov_b32 s8, 0
	global_load_dword v16, v2, s[12:13] sc1
	global_load_dword v17, v2, s[12:13] offset:256 sc1
	global_load_dword v18, v2, s[12:13] offset:512 sc1
	global_load_dword v19, v2, s[12:13] offset:768 sc1
	global_load_dword v20, v2, s[12:13] offset:1024 sc1
	global_load_dword v21, v2, s[12:13] offset:1280 sc1
	global_load_dword v22, v2, s[12:13] offset:1536 sc1
	global_load_dword v23, v2, s[12:13] offset:1792 sc1
	global_load_dword v24, v2, s[12:13] offset:2048 sc1
	global_load_dword v25, v2, s[12:13] offset:2304 sc1
	global_load_dword v26, v2, s[12:13] offset:2560 sc1
	global_load_dword v27, v2, s[12:13] offset:2816 sc1
	global_load_dword v28, v2, s[12:13] offset:3072 sc1
	global_load_dword v29, v2, s[12:13] offset:3328 sc1
	global_load_dword v30, v2, s[12:13] offset:3584 sc1
	global_load_dword v31, v2, s[12:13] offset:3840 sc1
	s_waitcnt vmcnt(0)
	v_cmp_ne_u32_e32 vcc, 0, v16
	s_cmp_lg_u64 vcc, 0
	s_addc_u32 s8, s8, 0
	s_cmp_eq_u32 s10, 0
	s_cselect_b64 vcc, -1, 0
	v_add_u32_e32 v3, v16, v3
	s_nop 1
	v_cndmask_b32_e32 v1, v1, v16, vcc
	v_cmp_ne_u32_e32 vcc, 0, v17
	s_cmp_lg_u64 vcc, 0
	s_addc_u32 s8, s8, 0
	s_cmp_eq_u32 s10, 0x100
	s_cselect_b64 vcc, -1, 0
	v_add_u32_e32 v3, v17, v3
	s_nop 1
	v_cndmask_b32_e32 v1, v1, v17, vcc
	v_cmp_ne_u32_e32 vcc, 0, v18
	s_cmp_lg_u64 vcc, 0
	s_addc_u32 s8, s8, 0
	s_cmp_eq_u32 s10, 0x200
	s_cselect_b64 vcc, -1, 0
	v_add_u32_e32 v3, v18, v3
	s_nop 1
	v_cndmask_b32_e32 v1, v1, v18, vcc
	v_cmp_ne_u32_e32 vcc, 0, v19
	s_cmp_lg_u64 vcc, 0
	s_addc_u32 s8, s8, 0
	s_cmp_eq_u32 s10, 0x300
	s_cselect_b64 vcc, -1, 0
	v_add_u32_e32 v3, v19, v3
	s_nop 1
	v_cndmask_b32_e32 v1, v1, v19, vcc
	v_cmp_ne_u32_e32 vcc, 0, v20
	s_cmp_lg_u64 vcc, 0
	s_addc_u32 s8, s8, 0
	s_cmp_eq_u32 s10, 0x400
	s_cselect_b64 vcc, -1, 0
	v_add_u32_e32 v3, v20, v3
	s_nop 1
	v_cndmask_b32_e32 v1, v1, v20, vcc
	v_cmp_ne_u32_e32 vcc, 0, v21
	s_cmp_lg_u64 vcc, 0
	s_addc_u32 s8, s8, 0
	s_cmp_eq_u32 s10, 0x500
	s_cselect_b64 vcc, -1, 0
	v_add_u32_e32 v3, v21, v3
	s_nop 1
	v_cndmask_b32_e32 v1, v1, v21, vcc
	v_cmp_ne_u32_e32 vcc, 0, v22
	s_cmp_lg_u64 vcc, 0
	s_addc_u32 s8, s8, 0
	s_cmp_eq_u32 s10, 0x600
	s_cselect_b64 vcc, -1, 0
	v_add_u32_e32 v3, v22, v3
	s_nop 1
	v_cndmask_b32_e32 v1, v1, v22, vcc
	v_cmp_ne_u32_e32 vcc, 0, v23
	s_cmp_lg_u64 vcc, 0
	s_addc_u32 s8, s8, 0
	s_cmp_eq_u32 s10, 0x700
	s_cselect_b64 vcc, -1, 0
	v_add_u32_e32 v3, v23, v3
	s_nop 1
	v_cndmask_b32_e32 v1, v1, v23, vcc
	v_cmp_ne_u32_e32 vcc, 0, v24
	s_cmp_lg_u64 vcc, 0
	s_addc_u32 s8, s8, 0
	s_cmp_eq_u32 s10, 0x800
	s_cselect_b64 vcc, -1, 0
	v_add_u32_e32 v3, v24, v3
	s_nop 1
	v_cndmask_b32_e32 v1, v1, v24, vcc
	v_cmp_ne_u32_e32 vcc, 0, v25
	s_cmp_lg_u64 vcc, 0
	s_addc_u32 s8, s8, 0
	s_cmp_eq_u32 s10, 0x900
	s_cselect_b64 vcc, -1, 0
	v_add_u32_e32 v3, v25, v3
	s_nop 1
	v_cndmask_b32_e32 v1, v1, v25, vcc
	v_cmp_ne_u32_e32 vcc, 0, v26
	s_cmp_lg_u64 vcc, 0
	s_addc_u32 s8, s8, 0
	s_cmp_eq_u32 s10, 0xa00
	s_cselect_b64 vcc, -1, 0
	v_add_u32_e32 v3, v26, v3
	s_nop 1
	v_cndmask_b32_e32 v1, v1, v26, vcc
	v_cmp_ne_u32_e32 vcc, 0, v27
	s_cmp_lg_u64 vcc, 0
	s_addc_u32 s8, s8, 0
	s_cmp_eq_u32 s10, 0xb00
	s_cselect_b64 vcc, -1, 0
	v_add_u32_e32 v3, v27, v3
	s_nop 1
	v_cndmask_b32_e32 v1, v1, v27, vcc
	v_cmp_ne_u32_e32 vcc, 0, v28
	s_cmp_lg_u64 vcc, 0
	s_addc_u32 s8, s8, 0
	s_cmp_eq_u32 s10, 0xc00
	s_cselect_b64 vcc, -1, 0
	v_add_u32_e32 v3, v28, v3
	s_nop 1
	v_cndmask_b32_e32 v1, v1, v28, vcc
	v_cmp_ne_u32_e32 vcc, 0, v29
	s_cmp_lg_u64 vcc, 0
	s_addc_u32 s8, s8, 0
	s_cmp_eq_u32 s10, 0xd00
	s_cselect_b64 vcc, -1, 0
	v_add_u32_e32 v3, v29, v3
	s_nop 1
	v_cndmask_b32_e32 v1, v1, v29, vcc
	v_cmp_ne_u32_e32 vcc, 0, v30
	s_cmp_lg_u64 vcc, 0
	s_addc_u32 s8, s8, 0
	s_cmp_eq_u32 s10, 0xe00
	s_cselect_b64 vcc, -1, 0
	v_add_u32_e32 v3, v30, v3
	s_nop 1
	v_cndmask_b32_e32 v1, v1, v30, vcc
	v_cmp_ne_u32_e32 vcc, 0, v31
	s_cmp_lg_u64 vcc, 0
	s_addc_u32 s8, s8, 0
	s_cmp_eq_u32 s10, 0xf00
	s_cselect_b64 vcc, -1, 0
	v_add_u32_e32 v3, v31, v3
	s_nop 1
	v_cndmask_b32_e32 v1, v1, v31, vcc
	v_cmp_ne_u32_e32 vcc, s11, v3
	s_mov_b64 s[4:5], -1
	s_mov_b64 s[6:7], -1
	s_cbranch_vccz .LBB0_635
	s_add_i32 s9, s9, 1
	s_and_b32 s6, s9, 0xff
	s_cmp_eq_u32 s6, 0
	s_cselect_b64 s[6:7], -1, 0
	s_and_b64 vcc, exec, s[6:7]
	s_sleep 1
	s_cbranch_vccz .LBB0_635
	global_load_dword v3, v2, s[2:3] sc1
	s_waitcnt vmcnt(0)
	v_cmp_eq_u32_e32 vcc, 0, v3
	s_cbranch_vccz .LBB0_635
	s_cmp_gt_u32 s9, 0x40000
	s_mov_b64 s[4:5], 0
	s_cselect_b64 s[6:7], -1, 0
	s_branch .LBB0_635
